# attention softmax: 36 serialized exec-masked bias ds_read_b32+wait replaced by 36 up-front unconditional reads into dead K-fragment VGPRs
# speedup vs baseline: 1.0002x; 1.0002x over previous
.LBB0_324:
	s_add_i32 vcc_lo, s37, -1
	s_and_b32 s39, vcc_lo, s36
	s_not_b32 s0, s39
	s_add_i32 s1, s33, s0
	s_lshl_b32 s1, s1, 7
	s_and_b32 s1, s1, 0x80
	v_or_b32_e32 v60, s1, v187
	v_readlane_b32 s1, v255, 19
	s_add_i32 s1, s1, s0
	s_lshl_b32 s1, s1, 7
	s_and_b32 s1, s1, 0x80
	v_or_b32_e32 v88, s1, v188
	v_lshl_add_u32 v68, v60, 8, 0
	v_lshl_add_u32 v96, v88, 8, 0
	v_add_u32_e32 v60, v68, v147
	v_add_u32_e32 v64, v68, v148
	v_add_u32_e32 v69, v68, v149
	v_add_u32_e32 v76, v68, v150
	v_add_u32_e32 v88, v96, v147
	v_add_u32_e32 v92, v96, v148
	v_add_u32_e32 v97, v96, v149
	ds_read_b128 v[60:63], v60
	ds_read_b128 v[64:67], v64
	ds_read_b128 v[68:71], v69
	ds_read_b128 v[76:79], v76
	ds_read_b128 v[88:91], v88
	ds_read_b128 v[92:95], v92
	v_add_u32_e32 v100, v96, v150
	ds_read_b128 v[96:99], v97
	ds_read_b128 v[220:223], v100
	s_waitcnt lgkmcnt(7)
	v_mfma_f32_16x16x32_bf16 v[60:63], v[60:63], v[56:59], 0
	s_waitcnt lgkmcnt(6)
	v_mfma_f32_16x16x32_bf16 v[60:63], v[64:67], v[72:75], v[60:63]
	s_waitcnt lgkmcnt(5)
	v_mfma_f32_16x16x32_bf16 v[60:63], v[68:71], v[80:83], v[60:63]
	s_waitcnt lgkmcnt(4)
	v_mfma_f32_16x16x32_bf16 v[100:103], v[76:79], v[84:87], v[60:63]
	s_add_i32 s1, s17, s0
	s_lshl_b32 s1, s1, 7
	s_and_b32 s1, s1, 0x80
	s_nop 2
	v_or_b32_e32 v60, s1, v189
	v_lshl_add_u32 v68, v60, 8, 0
	v_add_u32_e32 v60, v68, v147
	v_add_u32_e32 v64, v68, v148
	v_add_u32_e32 v69, v68, v149
	v_add_u32_e32 v76, v68, v150
	ds_read_b128 v[60:63], v60
	ds_read_b128 v[64:67], v64
	ds_read_b128 v[68:71], v69
	ds_read_b128 v[76:79], v76
	s_waitcnt lgkmcnt(7)
	v_mfma_f32_16x16x32_bf16 v[88:91], v[88:91], v[56:59], 0
	s_waitcnt lgkmcnt(6)
	v_mfma_f32_16x16x32_bf16 v[88:91], v[92:95], v[72:75], v[88:91]
	s_waitcnt lgkmcnt(5)
	v_mfma_f32_16x16x32_bf16 v[88:91], v[96:99], v[80:83], v[88:91]
	s_waitcnt lgkmcnt(4)
	v_mfma_f32_16x16x32_bf16 v[96:99], v[220:223], v[84:87], v[88:91]
	v_readlane_b32 s1, v255, 21
	s_add_i32 s1, s1, s0
	s_lshl_b32 s1, s1, 7
	s_and_b32 s1, s1, 0x80
	s_nop 1
	v_or_b32_e32 v88, s1, v190
	v_lshl_add_u32 v92, v88, 8, 0
	v_add_u32_e32 v88, v92, v147
	v_add_u32_e32 v93, v92, v148
	ds_read_b128 v[88:91], v88
	ds_read_b128 v[220:223], v93
	v_add_u32_e32 v93, v92, v149
	v_add_u32_e32 v92, v92, v150
	ds_read_b128 v[224:227], v93
	ds_read_b128 v[228:231], v92
	s_waitcnt lgkmcnt(7)
	v_mfma_f32_16x16x32_bf16 v[60:63], v[60:63], v[56:59], 0
	s_waitcnt lgkmcnt(6)
	v_mfma_f32_16x16x32_bf16 v[60:63], v[64:67], v[72:75], v[60:63]
	s_waitcnt lgkmcnt(5)
	v_mfma_f32_16x16x32_bf16 v[60:63], v[68:71], v[80:83], v[60:63]
	s_waitcnt lgkmcnt(4)
	v_mfma_f32_16x16x32_bf16 v[92:95], v[76:79], v[84:87], v[60:63]
	s_add_i32 s1, s18, s0
	s_lshl_b32 s1, s1, 7
	s_and_b32 s1, s1, 0x80
	s_nop 2
	v_or_b32_e32 v60, s1, v191
	v_lshl_add_u32 v68, v60, 8, 0
	v_add_u32_e32 v60, v68, v147
	v_add_u32_e32 v64, v68, v148
	v_add_u32_e32 v69, v68, v149
	v_add_u32_e32 v76, v68, v150
	ds_read_b128 v[60:63], v60
	ds_read_b128 v[64:67], v64
	ds_read_b128 v[68:71], v69
	ds_read_b128 v[76:79], v76
	s_waitcnt lgkmcnt(7)
	v_mfma_f32_16x16x32_bf16 v[88:91], v[88:91], v[56:59], 0
	s_waitcnt lgkmcnt(6)
	v_mfma_f32_16x16x32_bf16 v[88:91], v[220:223], v[72:75], v[88:91]
	s_waitcnt lgkmcnt(5)
	v_mfma_f32_16x16x32_bf16 v[88:91], v[224:227], v[80:83], v[88:91]
	s_waitcnt lgkmcnt(4)
	v_mfma_f32_16x16x32_bf16 v[88:91], v[228:231], v[84:87], v[88:91]
	v_readlane_b32 s1, v255, 23
	s_add_i32 s1, s1, s0
	s_lshl_b32 s1, s1, 7
	s_and_b32 s1, s1, 0x80
	v_or_b32_e32 v109, s1, v204
	v_lshl_add_u32 v109, v109, 8, 0
	v_add_u32_e32 v111, v109, v147
	v_add_u32_e32 v196, v109, v148
	ds_read_b128 v[220:223], v111
	ds_read_b128 v[224:227], v196
	v_add_u32_e32 v111, v109, v149
	v_add_u32_e32 v109, v109, v150
	ds_read_b128 v[228:231], v111
	ds_read_b128 v[238:241], v109
	s_waitcnt lgkmcnt(7)
	v_mfma_f32_16x16x32_bf16 v[60:63], v[60:63], v[56:59], 0
	s_waitcnt lgkmcnt(6)
	v_mfma_f32_16x16x32_bf16 v[60:63], v[64:67], v[72:75], v[60:63]
	s_waitcnt lgkmcnt(5)
	v_mfma_f32_16x16x32_bf16 v[60:63], v[68:71], v[80:83], v[60:63]
	s_waitcnt lgkmcnt(4)
	v_mfma_f32_16x16x32_bf16 v[76:79], v[76:79], v[84:87], v[60:63]
	s_add_i32 s1, s19, s0
	s_lshl_b32 s1, s1, 7
	s_and_b32 s1, s1, 0x80
	s_nop 2
	v_or_b32_e32 v60, s1, v205
	v_lshl_add_u32 v68, v60, 8, 0
	v_add_u32_e32 v60, v68, v147
	v_add_u32_e32 v64, v68, v148
	v_add_u32_e32 v69, v68, v149
	ds_read_b128 v[60:63], v60
	ds_read_b128 v[64:67], v64
	v_add_u32_e32 v68, v68, v150
	ds_read_b128 v[242:245], v69
	ds_read_b128 v[246:249], v68
	s_waitcnt lgkmcnt(7)
	v_mfma_f32_16x16x32_bf16 v[68:71], v[220:223], v[56:59], 0
	s_waitcnt lgkmcnt(6)
	v_mfma_f32_16x16x32_bf16 v[68:71], v[224:227], v[72:75], v[68:71]
	s_waitcnt lgkmcnt(5)
	v_mfma_f32_16x16x32_bf16 v[68:71], v[228:231], v[80:83], v[68:71]
	s_waitcnt lgkmcnt(4)
	v_mfma_f32_16x16x32_bf16 v[68:71], v[238:241], v[84:87], v[68:71]
	v_readlane_b32 s1, v255, 25
	s_add_i32 s1, s1, s0
	s_lshl_b32 s1, s1, 7
	s_and_b32 s1, s1, 0x80
	v_or_b32_e32 v109, s1, v206
	v_lshl_add_u32 v109, v109, 8, 0
	v_add_u32_e32 v111, v109, v147
	v_add_u32_e32 v196, v109, v148
	ds_read_b128 v[220:223], v111
	ds_read_b128 v[224:227], v196
	v_add_u32_e32 v111, v109, v149
	v_add_u32_e32 v109, v109, v150
	ds_read_b128 v[228:231], v111
	ds_read_b128 v[238:241], v109
	s_waitcnt lgkmcnt(7)
	v_mfma_f32_16x16x32_bf16 v[60:63], v[60:63], v[56:59], 0
	s_waitcnt lgkmcnt(6)
	v_mfma_f32_16x16x32_bf16 v[60:63], v[64:67], v[72:75], v[60:63]
	s_waitcnt lgkmcnt(5)
	v_mfma_f32_16x16x32_bf16 v[60:63], v[242:245], v[80:83], v[60:63]
	s_waitcnt lgkmcnt(4)
	v_mfma_f32_16x16x32_bf16 v[64:67], v[246:249], v[84:87], v[60:63]
	s_add_i32 s0, s20, s0
	s_lshl_b32 s0, s0, 7
	s_and_b32 s0, s0, 0x80
	s_nop 2
	v_or_b32_e32 v60, s0, v207
	v_lshl_add_u32 v60, v60, 8, 0
	v_add_u32_e32 v61, v60, v147
	v_add_u32_e32 v62, v60, v148
	ds_read_b128 v[242:245], v61
	ds_read_b128 v[246:249], v62
	v_add_u32_e32 v61, v60, v149
	v_add_u32_e32 v60, v60, v150
	ds_read_b128 v[250:253], v61
	ds_read_b128 v[196:199], v60
	s_waitcnt lgkmcnt(7)
	v_mfma_f32_16x16x32_bf16 v[60:63], v[220:223], v[56:59], 0
	s_waitcnt lgkmcnt(6)
	v_mfma_f32_16x16x32_bf16 v[60:63], v[224:227], v[72:75], v[60:63]
	s_waitcnt lgkmcnt(5)
	v_mfma_f32_16x16x32_bf16 v[60:63], v[228:231], v[80:83], v[60:63]
	s_waitcnt lgkmcnt(4)
	v_mfma_f32_16x16x32_bf16 v[60:63], v[238:241], v[84:87], v[60:63]
	s_waitcnt lgkmcnt(3)
	v_mfma_f32_16x16x32_bf16 v[56:59], v[242:245], v[56:59], 0
	s_waitcnt lgkmcnt(2)
	v_mfma_f32_16x16x32_bf16 v[56:59], v[246:249], v[72:75], v[56:59]
	s_waitcnt lgkmcnt(1)
	v_mfma_f32_16x16x32_bf16 v[56:59], v[250:253], v[80:83], v[56:59]
	s_waitcnt lgkmcnt(0)
	v_mfma_f32_16x16x32_bf16 v[56:59], v[196:199], v[84:87], v[56:59]
	ds_read_b32 v40, v151
	ds_read_b32 v41, v152
	ds_read_b32 v42, v153
	ds_read_b32 v43, v154
	ds_read_b32 v44, v155
	ds_read_b32 v45, v157
	ds_read_b32 v46, v158
	ds_read_b32 v47, v159
	ds_read_b32 v48, v160
	ds_read_b32 v49, v161
	ds_read_b32 v50, v162
	ds_read_b32 v51, v163
	ds_read_b32 v52, v164
	ds_read_b32 v53, v165
	ds_read_b32 v54, v166
	ds_read_b32 v55, v167
	ds_read_b32 v220, v168
	ds_read_b32 v221, v169
	ds_read_b32 v222, v170
	ds_read_b32 v223, v171
	ds_read_b32 v224, v172
	ds_read_b32 v225, v173
	ds_read_b32 v226, v174
	ds_read_b32 v227, v175
	ds_read_b32 v228, v176
	ds_read_b32 v229, v177
	ds_read_b32 v230, v178
	ds_read_b32 v231, v179
	ds_read_b32 v238, v180
	ds_read_b32 v239, v181
	ds_read_b32 v240, v182
	ds_read_b32 v241, v183
	ds_read_b32 v242, v156
	ds_read_b32 v243, v184
	ds_read_b32 v244, v185
	ds_read_b32 v245, v186
	s_cmp_lg_u32 s39, 0
	v_readlane_b32 s10, v255, 29
	s_cselect_b64 s[0:1], -1, 0
	v_readlane_b32 s11, v255, 30
	v_readlane_b32 s40, v255, 27
	s_or_b64 s[10:11], s[0:1], s[10:11]
	v_readlane_b32 s41, v255, 28
	s_and_b64 s[40:41], s[40:41], s[10:11]
	v_mov_b32_e32 v75, 0xf149f2ca
	v_mov_b32_e32 v81, 0xf149f2ca
	s_and_saveexec_b64 s[10:11], s[40:41]
	s_waitcnt lgkmcnt(0)
	v_add_f32_e32 v81, v100, v40
	s_or_b64 exec, exec, s[10:11]
	v_readlane_b32 s10, v255, 33
	v_readlane_b32 s11, v255, 34
	v_readlane_b32 s40, v255, 31
	s_or_b64 s[10:11], s[0:1], s[10:11]
	v_readlane_b32 s41, v255, 32
	s_and_b64 s[40:41], s[40:41], s[10:11]
	s_and_saveexec_b64 s[10:11], s[40:41]
	s_waitcnt lgkmcnt(0)
	v_add_f32_e32 v75, v101, v41
	s_or_b64 exec, exec, s[10:11]
	v_readlane_b32 s10, v255, 37
	v_readlane_b32 s11, v255, 38
	v_readlane_b32 s40, v255, 35
	s_or_b64 s[10:11], s[0:1], s[10:11]
	v_readlane_b32 s41, v255, 36
	s_and_b64 s[40:41], s[40:41], s[10:11]
	v_mov_b32_e32 v82, 0xf149f2ca
	v_mov_b32_e32 v85, 0xf149f2ca
	s_and_saveexec_b64 s[10:11], s[40:41]
	s_waitcnt lgkmcnt(0)
	v_add_f32_e32 v85, v102, v42
	s_or_b64 exec, exec, s[10:11]
	v_readlane_b32 s10, v255, 41
	v_readlane_b32 s11, v255, 42
	v_readlane_b32 s40, v255, 39
	s_or_b64 s[10:11], s[0:1], s[10:11]
	v_readlane_b32 s41, v255, 40
	s_and_b64 s[40:41], s[40:41], s[10:11]
	s_and_saveexec_b64 s[10:11], s[40:41]
	s_waitcnt lgkmcnt(0)
	v_add_f32_e32 v82, v103, v43
	s_or_b64 exec, exec, s[10:11]
	v_readlane_b32 s10, v255, 43
	v_readlane_b32 s11, v255, 44
	s_or_b64 s[40:41], s[0:1], s[10:11]
	v_mov_b32_e32 v86, 0xf149f2ca
	v_mov_b32_e32 v100, 0xf149f2ca
	s_and_saveexec_b64 s[10:11], s[40:41]
	s_waitcnt lgkmcnt(0)
	v_add_f32_e32 v100, v96, v44
	s_or_b64 exec, exec, s[10:11]
	v_readlane_b32 s10, v255, 45
	v_readlane_b32 s11, v255, 46
	s_or_b64 s[40:41], s[0:1], s[10:11]
	s_and_saveexec_b64 s[10:11], s[40:41]
	s_waitcnt lgkmcnt(0)
	v_add_f32_e32 v86, v97, v45
	s_or_b64 exec, exec, s[10:11]
	v_readlane_b32 s10, v255, 47
	v_readlane_b32 s11, v255, 48
	s_or_b64 s[40:41], s[0:1], s[10:11]
	v_mov_b32_e32 v80, 0xf149f2ca
	v_mov_b32_e32 v96, 0xf149f2ca
	s_and_saveexec_b64 s[10:11], s[40:41]
	s_waitcnt lgkmcnt(0)
	v_add_f32_e32 v96, v98, v46
	s_or_b64 exec, exec, s[10:11]
	v_readlane_b32 s10, v255, 49
	v_readlane_b32 s11, v255, 50
	s_or_b64 s[40:41], s[0:1], s[10:11]
	s_and_saveexec_b64 s[10:11], s[40:41]
	s_waitcnt lgkmcnt(0)
	v_add_f32_e32 v80, v99, v47
	s_or_b64 exec, exec, s[10:11]
	v_readlane_b32 s10, v255, 51
	v_readlane_b32 s11, v255, 52
	s_or_b64 s[40:41], s[0:1], s[10:11]
	v_mov_b32_e32 v83, 0xf149f2ca
	v_mov_b32_e32 v84, 0xf149f2ca
	s_and_saveexec_b64 s[10:11], s[40:41]
	s_waitcnt lgkmcnt(0)
	v_add_f32_e32 v84, v92, v48
	s_or_b64 exec, exec, s[10:11]
	v_readlane_b32 s10, v255, 53
	v_readlane_b32 s11, v255, 54
	s_or_b64 s[40:41], s[0:1], s[10:11]
	s_and_saveexec_b64 s[10:11], s[40:41]
	s_waitcnt lgkmcnt(0)
	v_add_f32_e32 v83, v93, v49
	s_or_b64 exec, exec, s[10:11]
	v_readlane_b32 s10, v255, 55
	v_readlane_b32 s11, v255, 56
	s_or_b64 s[40:41], s[0:1], s[10:11]
	v_mov_b32_e32 v87, 0xf149f2ca
	v_mov_b32_e32 v92, 0xf149f2ca
	s_and_saveexec_b64 s[10:11], s[40:41]
	s_waitcnt lgkmcnt(0)
	v_add_f32_e32 v92, v94, v50
	s_or_b64 exec, exec, s[10:11]
	v_readlane_b32 s10, v255, 57
	v_readlane_b32 s11, v255, 58
	s_or_b64 s[40:41], s[0:1], s[10:11]
	s_and_saveexec_b64 s[10:11], s[40:41]
	s_waitcnt lgkmcnt(0)
	v_add_f32_e32 v87, v95, v51
	s_or_b64 exec, exec, s[10:11]
	v_readlane_b32 s10, v255, 59
	v_readlane_b32 s11, v255, 60
	s_or_b64 s[40:41], s[0:1], s[10:11]
	v_mov_b32_e32 v93, 0xf149f2ca
	v_mov_b32_e32 v94, 0xf149f2ca
	s_and_saveexec_b64 s[10:11], s[40:41]
	s_waitcnt lgkmcnt(0)
	v_add_f32_e32 v94, v88, v52
	s_or_b64 exec, exec, s[10:11]
	v_readlane_b32 s10, v255, 61
	v_readlane_b32 s11, v255, 62
	s_or_b64 s[40:41], s[0:1], s[10:11]
	s_and_saveexec_b64 s[10:11], s[40:41]
	s_waitcnt lgkmcnt(0)
	v_add_f32_e32 v93, v89, v53
	s_or_b64 exec, exec, s[10:11]
	s_or_b64 s[40:41], s[0:1], s[52:53]
	v_mov_b32_e32 v88, 0xf149f2ca
	v_mov_b32_e32 v95, 0xf149f2ca
	s_and_saveexec_b64 s[10:11], s[40:41]
	s_waitcnt lgkmcnt(0)
	v_add_f32_e32 v95, v90, v54
	s_or_b64 exec, exec, s[10:11]
	s_or_b64 s[40:41], s[0:1], s[54:55]
	s_and_saveexec_b64 s[10:11], s[40:41]
	s_waitcnt lgkmcnt(0)
	v_add_f32_e32 v88, v91, v55
	s_or_b64 exec, exec, s[10:11]
	s_or_b64 s[40:41], s[0:1], s[56:57]
	v_mov_b32_e32 v89, 0xf149f2ca
	v_mov_b32_e32 v90, 0xf149f2ca
	s_and_saveexec_b64 s[10:11], s[40:41]
	s_waitcnt lgkmcnt(0)
	v_add_f32_e32 v90, v76, v220
	s_or_b64 exec, exec, s[10:11]
	s_or_b64 s[40:41], s[0:1], s[58:59]
	s_and_saveexec_b64 s[10:11], s[40:41]
	s_waitcnt lgkmcnt(0)
	v_add_f32_e32 v89, v77, v221
	s_or_b64 exec, exec, s[10:11]
	s_or_b64 s[40:41], s[0:1], s[60:61]
	v_mov_b32_e32 v76, 0xf149f2ca
	v_mov_b32_e32 v91, 0xf149f2ca
	s_and_saveexec_b64 s[10:11], s[40:41]
	s_waitcnt lgkmcnt(0)
	v_add_f32_e32 v91, v78, v222
	s_or_b64 exec, exec, s[10:11]
	s_or_b64 s[40:41], s[0:1], s[62:63]
	s_and_saveexec_b64 s[10:11], s[40:41]
	s_waitcnt lgkmcnt(0)
	v_add_f32_e32 v76, v79, v223
	s_or_b64 exec, exec, s[10:11]
	s_or_b64 s[40:41], s[0:1], s[64:65]
	v_mov_b32_e32 v77, 0xf149f2ca
	v_mov_b32_e32 v78, 0xf149f2ca
	s_and_saveexec_b64 s[10:11], s[40:41]
	s_waitcnt lgkmcnt(0)
	v_add_f32_e32 v78, v68, v224
	s_or_b64 exec, exec, s[10:11]
	s_or_b64 s[40:41], s[0:1], s[66:67]
	s_and_saveexec_b64 s[10:11], s[40:41]
	s_waitcnt lgkmcnt(0)
	v_add_f32_e32 v77, v69, v225
	s_or_b64 exec, exec, s[10:11]
	s_or_b64 s[40:41], s[0:1], s[68:69]
	v_mov_b32_e32 v68, 0xf149f2ca
	v_mov_b32_e32 v79, 0xf149f2ca
	s_and_saveexec_b64 s[10:11], s[40:41]
	s_waitcnt lgkmcnt(0)
	v_add_f32_e32 v79, v70, v226
	s_or_b64 exec, exec, s[10:11]
	s_or_b64 s[40:41], s[0:1], s[70:71]
	s_and_saveexec_b64 s[10:11], s[40:41]
	s_waitcnt lgkmcnt(0)
	v_add_f32_e32 v68, v71, v227
	s_or_b64 exec, exec, s[10:11]
	s_or_b64 s[40:41], s[0:1], s[72:73]
	v_mov_b32_e32 v69, 0xf149f2ca
	v_mov_b32_e32 v70, 0xf149f2ca
	s_and_saveexec_b64 s[10:11], s[40:41]
	s_waitcnt lgkmcnt(0)
	v_add_f32_e32 v70, v64, v228
	s_or_b64 exec, exec, s[10:11]
	s_or_b64 s[40:41], s[0:1], s[74:75]
	s_and_saveexec_b64 s[10:11], s[40:41]
	s_waitcnt lgkmcnt(0)
	v_add_f32_e32 v69, v65, v229
	s_or_b64 exec, exec, s[10:11]
	s_or_b64 s[40:41], s[0:1], s[76:77]
	v_mov_b32_e32 v64, 0xf149f2ca
	v_mov_b32_e32 v71, 0xf149f2ca
	s_and_saveexec_b64 s[10:11], s[40:41]
	s_waitcnt lgkmcnt(0)
	v_add_f32_e32 v71, v66, v230
	s_or_b64 exec, exec, s[10:11]
	s_or_b64 s[40:41], s[0:1], s[78:79]
	s_and_saveexec_b64 s[10:11], s[40:41]
	s_waitcnt lgkmcnt(0)
	v_add_f32_e32 v64, v67, v231
	s_or_b64 exec, exec, s[10:11]
	s_or_b64 s[40:41], s[0:1], s[80:81]
	v_mov_b32_e32 v65, 0xf149f2ca
	v_mov_b32_e32 v66, 0xf149f2ca
	s_and_saveexec_b64 s[10:11], s[40:41]
	s_waitcnt lgkmcnt(0)
	v_add_f32_e32 v66, v60, v238
	s_or_b64 exec, exec, s[10:11]
	s_or_b64 s[40:41], s[0:1], s[82:83]
	s_and_saveexec_b64 s[10:11], s[40:41]
	s_waitcnt lgkmcnt(0)
	v_add_f32_e32 v65, v61, v239
	s_or_b64 exec, exec, s[10:11]
	s_or_b64 s[40:41], s[0:1], s[84:85]
	v_mov_b32_e32 v60, 0xf149f2ca
	v_mov_b32_e32 v61, 0xf149f2ca
	s_and_saveexec_b64 s[10:11], s[40:41]
	s_waitcnt lgkmcnt(0)
	v_add_f32_e32 v61, v62, v240
	s_or_b64 exec, exec, s[10:11]
	s_or_b64 s[40:41], s[0:1], s[86:87]
	s_and_saveexec_b64 s[10:11], s[40:41]
	s_waitcnt lgkmcnt(0)
	v_add_f32_e32 v60, v63, v241
	s_or_b64 exec, exec, s[10:11]
	s_or_b64 s[10:11], s[0:1], s[90:91]
	s_and_b64 s[40:41], s[88:89], s[10:11]
	v_mov_b32_e32 v62, 0xf149f2ca
	v_mov_b32_e32 v63, 0xf149f2ca
	s_and_saveexec_b64 s[10:11], s[40:41]
	s_waitcnt lgkmcnt(0)
	v_add_f32_e32 v63, v56, v242
	s_or_b64 exec, exec, s[10:11]
	s_or_b64 s[10:11], s[0:1], s[94:95]
	s_and_b64 s[40:41], s[92:93], s[10:11]
	s_and_saveexec_b64 s[10:11], s[40:41]
	s_waitcnt lgkmcnt(0)
	v_add_f32_e32 v62, v57, v243
	s_or_b64 exec, exec, s[10:11]
	s_or_b64 s[10:11], s[0:1], s[8:9]
	s_and_b64 s[40:41], s[96:97], s[10:11]
	v_mov_b32_e32 v56, 0xf149f2ca
	v_mov_b32_e32 v57, 0xf149f2ca
	s_and_saveexec_b64 s[10:11], s[40:41]
	s_waitcnt lgkmcnt(0)
	v_add_f32_e32 v57, v58, v244
	s_or_b64 exec, exec, s[10:11]
	s_or_b64 s[0:1], s[0:1], s[6:7]
	s_and_b64 s[10:11], s[4:5], s[0:1]
	s_and_saveexec_b64 s[0:1], s[10:11]
	s_waitcnt lgkmcnt(0)
	v_add_f32_e32 v56, v59, v245
	s_or_b64 exec, exec, s[0:1]
	s_mov_b32 s0, 0xff61b1e6
	v_max3_f32 v58, v81, s0, v75
	v_max3_f32 v58, v58, v85, v82
	v_max3_f32 v58, v58, v100, v86
	v_max3_f32 v58, v58, v96, v80
	v_max3_f32 v58, v58, v84, v83
	v_max3_f32 v58, v58, v92, v87
	v_max3_f32 v58, v58, v94, v93
	v_max3_f32 v58, v58, v95, v88
	v_max3_f32 v58, v58, v90, v89
	v_max3_f32 v58, v58, v91, v76
	v_max3_f32 v58, v58, v78, v77
	v_max3_f32 v58, v58, v79, v68
	v_max3_f32 v58, v58, v70, v69
	v_max3_f32 v58, v58, v71, v64
	v_max3_f32 v58, v58, v66, v65
	v_max3_f32 v58, v58, v61, v60
	v_max3_f32 v67, v58, v63, v62
	s_lshr_b32 s0, vcc_lo, s35
	v_lshl_add_u32 v58, s39, 7, v145
	v_ashrrev_i32_e32 v59, 31, v58
	s_add_u32 s0, s2, s0
	s_addc_u32 s1, s3, 0
	v_lshlrev_b64 v[58:59], s34, v[58:59]
	v_lshl_add_u64 v[72:73], s[0:1], 0, v[58:59]
	v_max3_f32 v58, v67, v57, v56
	ds_bpermute_b32 v59, v218, v58
	s_add_i32 s0, s39, 1
	v_readlane_b32 s10, v255, 13
	s_add_i32 s1, s0, s33
	s_add_i32 s10, s0, s10
	s_waitcnt lgkmcnt(0)
	v_max_f32_e32 v59, v59, v59
	v_max_f32_e32 v58, v58, v59
	ds_bpermute_b32 v59, v219, v58
	s_lshl_b32 s1, s1, 15
	s_lshl_b32 s10, s10, 15
	s_and_b32 s1, s1, 0x8000
	s_and_b32 s10, s10, 0x8000
	s_waitcnt lgkmcnt(0)
	v_max_f32_e32 v59, v59, v59
	v_max_f32_e32 v74, v58, v59
	v_sub_f32_e32 v58, v81, v74
	v_exp_f32_e32 v58, v58
	v_sub_f32_e32 v67, v75, v74
	v_exp_f32_e32 v67, v67
	v_sub_f32_e32 v75, v85, v74
	v_exp_f32_e32 v81, v75
	v_sub_f32_e32 v75, v82, v74
	v_exp_f32_e32 v82, v75
	v_sub_f32_e32 v75, v100, v74
	v_add_f32_e32 v59, 0, v58
	v_exp_f32_e32 v85, v75
	v_sub_f32_e32 v75, v86, v74
	v_add_f32_e32 v59, v67, v59
	v_exp_f32_e32 v86, v75
	v_sub_f32_e32 v75, v96, v74
	v_add_f32_e32 v59, v81, v59
	v_exp_f32_e32 v96, v75
	v_sub_f32_e32 v75, v80, v74
	v_add_f32_e32 v59, v82, v59
	v_exp_f32_e32 v97, v75
	v_sub_f32_e32 v75, v84, v74
	v_add_f32_e32 v59, v85, v59
	v_exp_f32_e32 v84, v75
	v_sub_f32_e32 v75, v83, v74
	v_add_f32_e32 v59, v86, v59
	v_exp_f32_e32 v83, v75
	v_sub_f32_e32 v75, v92, v74
	v_add_f32_e32 v59, v96, v59
	v_exp_f32_e32 v92, v75
	v_sub_f32_e32 v75, v87, v74
	v_add_f32_e32 v59, v97, v59
	v_exp_f32_e32 v87, v75
	v_sub_f32_e32 v75, v94, v74
	v_add_f32_e32 v59, v84, v59
	v_exp_f32_e32 v94, v75
	v_sub_f32_e32 v75, v93, v74
	v_add_f32_e32 v59, v83, v59
	v_exp_f32_e32 v93, v75
	v_sub_f32_e32 v75, v95, v74
	v_add_f32_e32 v59, v92, v59
	v_exp_f32_e32 v95, v75
	v_sub_f32_e32 v75, v88, v74
	v_add_f32_e32 v59, v87, v59
	v_exp_f32_e32 v88, v75
	v_sub_f32_e32 v75, v90, v74
	v_add_f32_e32 v59, v94, v59
	v_exp_f32_e32 v90, v75
	v_sub_f32_e32 v75, v89, v74
	v_add_f32_e32 v59, v93, v59
	v_exp_f32_e32 v89, v75
	v_sub_f32_e32 v75, v91, v74
	v_add_f32_e32 v59, v95, v59
	v_exp_f32_e32 v91, v75
	v_sub_f32_e32 v75, v76, v74
	v_add_f32_e32 v59, v88, v59
	v_exp_f32_e32 v98, v75
	v_sub_f32_e32 v75, v78, v74
	v_add_f32_e32 v59, v90, v59
	v_exp_f32_e32 v99, v75
	v_sub_f32_e32 v75, v77, v74
	v_add_f32_e32 v59, v89, v59
	v_exp_f32_e32 v77, v75
	v_sub_f32_e32 v75, v79, v74
	v_add_f32_e32 v59, v91, v59
	v_exp_f32_e32 v100, v75
	v_sub_f32_e32 v68, v68, v74
	v_add_f32_e32 v59, v98, v59
	v_exp_f32_e32 v101, v68
	v_sub_f32_e32 v68, v70, v74
	v_add_f32_e32 v59, v99, v59
	v_exp_f32_e32 v102, v68
	v_sub_f32_e32 v68, v69, v74
	v_add_f32_e32 v59, v77, v59
	v_exp_f32_e32 v103, v68
	v_sub_f32_e32 v68, v71, v74
	v_add_f32_e32 v59, v100, v59
	v_exp_f32_e32 v109, v68
	v_sub_f32_e32 v64, v64, v74
	v_add_f32_e32 v59, v101, v59
	v_exp_f32_e32 v111, v64
	v_sub_f32_e32 v64, v66, v74
	v_add_f32_e32 v59, v102, v59
	v_exp_f32_e32 v196, v64
	v_sub_f32_e32 v64, v65, v74
	v_add_f32_e32 v59, v103, v59
	v_exp_f32_e32 v197, v64
	v_sub_f32_e32 v61, v61, v74
	v_add_f32_e32 v59, v109, v59
	v_exp_f32_e32 v198, v61
	v_sub_f32_e32 v60, v60, v74
	v_add_f32_e32 v59, v111, v59
	v_exp_f32_e32 v199, v60
	v_sub_f32_e32 v60, v63, v74
	v_add_f32_e32 v59, v196, v59
	v_exp_f32_e32 v220, v60
	v_sub_f32_e32 v60, v62, v74
	v_add_f32_e32 v59, v197, v59
	v_exp_f32_e32 v221, v60
	v_sub_f32_e32 v57, v57, v74
	v_add_f32_e32 v59, v198, v59
	v_exp_f32_e32 v57, v57
	v_sub_f32_e32 v56, v56, v74
	v_add_f32_e32 v59, v199, v59
	v_exp_f32_e32 v222, v56
	v_add_f32_e32 v59, v220, v59
	v_add_f32_e32 v59, v221, v59
	v_add_f32_e32 v59, v57, v59
	v_add_f32_e32 v56, v222, v59
	ds_bpermute_b32 v59, v218, v56
	v_readlane_b32 s11, v255, 15
	s_add_i32 s1, s16, s1
	s_add_i32 s10, s11, s10
	v_cvt_pk_bf16_f32 v78, v58, v67
	v_cvt_pk_bf16_f32 v79, v81, v82
	v_cvt_pk_bf16_f32 v80, v85, v86
	v_cvt_pk_bf16_f32 v81, v96, v97
	v_cvt_pk_bf16_f32 v68, v84, v83
	v_cvt_pk_bf16_f32 v69, v92, v87
	v_cvt_pk_bf16_f32 v70, v94, v93
	v_cvt_pk_bf16_f32 v71, v95, v88
	v_cvt_pk_bf16_f32 v64, v90, v89
	v_cvt_pk_bf16_f32 v65, v91, v98
	v_cvt_pk_bf16_f32 v66, v99, v77
	v_add_u32_e32 v77, s1, v129
	v_add_u32_e32 v84, s10, v129
	s_waitcnt lgkmcnt(0)
	v_add_f32_e32 v75, v56, v59
	v_cvt_pk_bf16_f32 v67, v100, v101
	v_cvt_pk_bf16_f32 v60, v102, v103
	v_cvt_pk_bf16_f32 v61, v109, v111
	v_cvt_pk_bf16_f32 v62, v196, v197
	v_cvt_pk_bf16_f32 v63, v198, v199
	v_cvt_pk_bf16_f32 v56, v220, v221
	v_cvt_pk_bf16_f32 v57, v57, v222
	v_cvt_pk_bf16_f32 v58, v193, v193
	v_cvt_pk_bf16_f32 v59, v193, v193
	ds_read_b64_tr_b16 v[82:83], v77
	ds_read_b64_tr_b16 v[84:85], v84
	v_add_u32_e32 v77, s1, v130
	v_add_u32_e32 v88, s10, v130
	ds_read_b64_tr_b16 v[86:87], v77
	ds_read_b64_tr_b16 v[88:89], v88
	v_add_u32_e32 v77, s1, v131
	v_add_u32_e32 v92, s10, v131
	ds_read_b64_tr_b16 v[90:91], v77
	ds_read_b64_tr_b16 v[92:93], v92
	v_add_u32_e32 v77, s1, v132
	v_add_u32_e32 v96, s10, v132
	ds_read_b64_tr_b16 v[94:95], v77
	ds_read_b64_tr_b16 v[96:97], v96
	ds_bpermute_b32 v76, v219, v75
	s_waitcnt lgkmcnt(7)
	v_mfma_f32_16x16x32_bf16 v[82:85], v[82:85], v[78:81], 0
	s_waitcnt lgkmcnt(5)
	v_mfma_f32_16x16x32_bf16 v[86:89], v[86:89], v[78:81], 0
	v_add_u32_e32 v77, s1, v133
	v_add_u32_e32 v100, s10, v133
	v_add_u32_e32 v102, s1, v134
	v_add_u32_e32 v103, s10, v134
	ds_read_b64_tr_b16 v[98:99], v77
	ds_read_b64_tr_b16 v[100:101], v100
	ds_read_b64_tr_b16 v[196:197], v102
	ds_read_b64_tr_b16 v[198:199], v103
	s_waitcnt lgkmcnt(7)
	v_mfma_f32_16x16x32_bf16 v[90:93], v[90:93], v[78:81], 0
	s_waitcnt lgkmcnt(5)
	v_mfma_f32_16x16x32_bf16 v[94:97], v[94:97], v[78:81], 0
	v_add_u32_e32 v77, s1, v135
	v_add_u32_e32 v102, s10, v135
	v_add_u32_e32 v103, s1, v136
	v_add_u32_e32 v109, s10, v136
	ds_read_b64_tr_b16 v[220:221], v77
	ds_read_b64_tr_b16 v[222:223], v102
	ds_read_b64_tr_b16 v[224:225], v103
	ds_read_b64_tr_b16 v[226:227], v109
	s_waitcnt lgkmcnt(6)
	v_mfma_f32_16x16x32_bf16 v[98:101], v[98:101], v[78:81], 0
	s_waitcnt lgkmcnt(4)
	v_mfma_f32_16x16x32_bf16 v[196:199], v[196:199], v[78:81], 0
	s_add_i32 s1, s0, s17
	s_lshl_b32 s1, s1, 15
	s_add_i32 s10, s0, s21
	s_and_b32 s1, s1, 0x8000
	s_lshl_b32 s10, s10, 15
	s_and_b32 s10, s10, 0x8000
	s_add_i32 s1, s22, s1
	s_add_i32 s10, s23, s10
	v_add_u32_e32 v77, s1, v129
	v_add_u32_e32 v102, s10, v129
	v_add_u32_e32 v103, s1, v130
	v_add_u32_e32 v109, s10, v130
	ds_read_b64_tr_b16 v[228:229], v77
	ds_read_b64_tr_b16 v[230:231], v102
	ds_read_b64_tr_b16 v[238:239], v103
	ds_read_b64_tr_b16 v[240:241], v109
	s_waitcnt lgkmcnt(6)
	v_mfma_f32_16x16x32_bf16 v[220:223], v[220:223], v[78:81], 0
	s_waitcnt lgkmcnt(4)
	v_mfma_f32_16x16x32_bf16 v[78:81], v[224:227], v[78:81], 0
	v_add_u32_e32 v77, s1, v131
	v_add_u32_e32 v102, s10, v131
	v_add_u32_e32 v103, s1, v132
	v_add_u32_e32 v109, s10, v132
	ds_read_b64_tr_b16 v[224:225], v77
	ds_read_b64_tr_b16 v[226:227], v102
	ds_read_b64_tr_b16 v[242:243], v103
	ds_read_b64_tr_b16 v[244:245], v109
	s_waitcnt lgkmcnt(6)
	v_mfma_f32_16x16x32_bf16 v[82:85], v[228:231], v[68:71], v[82:85]
	s_waitcnt lgkmcnt(4)
	v_mfma_f32_16x16x32_bf16 v[86:89], v[238:241], v[68:71], v[86:89]
	v_add_u32_e32 v77, s1, v133
	v_add_u32_e32 v102, s10, v133
	v_add_u32_e32 v103, s1, v134
	v_add_u32_e32 v109, s10, v134
	ds_read_b64_tr_b16 v[228:229], v77
	ds_read_b64_tr_b16 v[230:231], v102
	ds_read_b64_tr_b16 v[238:239], v103
	ds_read_b64_tr_b16 v[240:241], v109
	s_waitcnt lgkmcnt(6)
	v_mfma_f32_16x16x32_bf16 v[90:93], v[224:227], v[68:71], v[90:93]
	s_waitcnt lgkmcnt(4)
	v_mfma_f32_16x16x32_bf16 v[94:97], v[242:245], v[68:71], v[94:97]
	v_add_u32_e32 v77, s1, v135
	v_add_u32_e32 v102, s10, v135
	v_add_u32_e32 v103, s1, v136
	v_add_u32_e32 v109, s10, v136
	ds_read_b64_tr_b16 v[224:225], v77
	ds_read_b64_tr_b16 v[226:227], v102
	ds_read_b64_tr_b16 v[242:243], v103
	ds_read_b64_tr_b16 v[244:245], v109
	s_waitcnt lgkmcnt(6)
	v_mfma_f32_16x16x32_bf16 v[98:101], v[228:231], v[68:71], v[98:101]
	s_waitcnt lgkmcnt(4)
	v_mfma_f32_16x16x32_bf16 v[196:199], v[238:241], v[68:71], v[196:199]
	s_add_i32 s1, s0, s18
	s_lshl_b32 s1, s1, 15
	s_add_i32 s10, s0, s24
	s_and_b32 s1, s1, 0x8000
	s_lshl_b32 s10, s10, 15
	s_and_b32 s10, s10, 0x8000
	s_add_i32 s1, s25, s1
	s_add_i32 s10, s26, s10
	v_add_u32_e32 v77, s1, v129
	v_add_u32_e32 v102, s10, v129
	v_add_u32_e32 v103, s1, v130
	v_add_u32_e32 v109, s10, v130
	ds_read_b64_tr_b16 v[228:229], v77
	ds_read_b64_tr_b16 v[230:231], v102
	ds_read_b64_tr_b16 v[238:239], v103
	ds_read_b64_tr_b16 v[240:241], v109
	s_waitcnt lgkmcnt(6)
	v_mfma_f32_16x16x32_bf16 v[220:223], v[224:227], v[68:71], v[220:223]
	s_waitcnt lgkmcnt(4)
	v_mfma_f32_16x16x32_bf16 v[68:71], v[242:245], v[68:71], v[78:81]
	v_add_u32_e32 v77, s1, v131
	s_nop 1
	v_add_u32_e32 v80, s10, v131
	v_add_u32_e32 v102, s1, v132
	v_add_u32_e32 v103, s10, v132
	ds_read_b64_tr_b16 v[78:79], v77
	ds_read_b64_tr_b16 v[80:81], v80
	ds_read_b64_tr_b16 v[224:225], v102
	ds_read_b64_tr_b16 v[226:227], v103
	s_waitcnt lgkmcnt(6)
	v_mfma_f32_16x16x32_bf16 v[82:85], v[228:231], v[64:67], v[82:85]
	s_waitcnt lgkmcnt(4)
	v_mfma_f32_16x16x32_bf16 v[86:89], v[238:241], v[64:67], v[86:89]
	v_add_u32_e32 v77, s1, v133
	v_add_u32_e32 v102, s10, v133
	v_add_u32_e32 v103, s1, v134
	v_add_u32_e32 v109, s10, v134
	ds_read_b64_tr_b16 v[228:229], v77
	ds_read_b64_tr_b16 v[230:231], v102
	ds_read_b64_tr_b16 v[238:239], v103
	ds_read_b64_tr_b16 v[240:241], v109
	s_waitcnt lgkmcnt(6)
	v_mfma_f32_16x16x32_bf16 v[78:81], v[78:81], v[64:67], v[90:93]
	s_waitcnt lgkmcnt(4)
	v_mfma_f32_16x16x32_bf16 v[90:93], v[224:227], v[64:67], v[94:97]
	v_add_u32_e32 v77, s1, v135
	s_nop 1
	v_add_u32_e32 v96, s10, v135
	v_add_u32_e32 v102, s1, v136
	v_add_u32_e32 v103, s10, v136
	ds_read_b64_tr_b16 v[94:95], v77
	ds_read_b64_tr_b16 v[96:97], v96
	ds_read_b64_tr_b16 v[224:225], v102
	ds_read_b64_tr_b16 v[226:227], v103
	s_waitcnt lgkmcnt(6)
	v_mfma_f32_16x16x32_bf16 v[98:101], v[228:231], v[64:67], v[98:101]
	s_waitcnt lgkmcnt(4)
	v_mfma_f32_16x16x32_bf16 v[196:199], v[238:241], v[64:67], v[196:199]
	s_add_i32 s1, s0, s19
	s_lshl_b32 s1, s1, 15
	s_add_i32 s10, s0, s27
	s_and_b32 s1, s1, 0x8000
	s_lshl_b32 s10, s10, 15
	s_and_b32 s10, s10, 0x8000
	s_add_i32 s1, s28, s1
	s_add_i32 s10, s29, s10
	v_add_u32_e32 v77, s1, v129
	v_add_u32_e32 v102, s10, v129
	v_add_u32_e32 v103, s1, v130
	v_add_u32_e32 v109, s10, v130
	ds_read_b64_tr_b16 v[228:229], v77
	ds_read_b64_tr_b16 v[230:231], v102
	ds_read_b64_tr_b16 v[238:239], v103
	ds_read_b64_tr_b16 v[240:241], v109
	s_waitcnt lgkmcnt(6)
	v_mfma_f32_16x16x32_bf16 v[94:97], v[94:97], v[64:67], v[220:223]
	s_waitcnt lgkmcnt(4)
	v_mfma_f32_16x16x32_bf16 v[64:67], v[224:227], v[64:67], v[68:71]
	s_nop 2
	v_add_u32_e32 v68, s1, v131
	v_add_u32_e32 v70, s10, v131
	v_add_u32_e32 v77, s1, v132
	v_add_u32_e32 v102, s10, v132
	ds_read_b64_tr_b16 v[68:69], v68
	ds_read_b64_tr_b16 v[70:71], v70
	ds_read_b64_tr_b16 v[220:221], v77
	ds_read_b64_tr_b16 v[222:223], v102
	s_waitcnt lgkmcnt(6)
	v_mfma_f32_16x16x32_bf16 v[82:85], v[228:231], v[60:63], v[82:85]
	s_waitcnt lgkmcnt(4)
	v_mfma_f32_16x16x32_bf16 v[86:89], v[238:241], v[60:63], v[86:89]
	v_add_u32_e32 v77, s1, v133
	v_add_u32_e32 v102, s10, v133
	v_add_u32_e32 v103, s1, v134
	v_add_u32_e32 v109, s10, v134
	ds_read_b64_tr_b16 v[224:225], v77
	ds_read_b64_tr_b16 v[226:227], v102
	ds_read_b64_tr_b16 v[228:229], v103
	ds_read_b64_tr_b16 v[230:231], v109
	s_waitcnt lgkmcnt(6)
	v_mfma_f32_16x16x32_bf16 v[68:71], v[68:71], v[60:63], v[78:81]
	s_waitcnt lgkmcnt(4)
	v_mfma_f32_16x16x32_bf16 v[78:81], v[220:223], v[60:63], v[90:93]
	v_add_u32_e32 v77, s1, v135
	s_nop 1
	v_add_u32_e32 v92, s10, v135
	v_add_u32_e32 v102, s1, v136
	v_add_u32_e32 v103, s10, v136
	ds_read_b64_tr_b16 v[90:91], v77
	ds_read_b64_tr_b16 v[92:93], v92
	ds_read_b64_tr_b16 v[220:221], v102
	ds_read_b64_tr_b16 v[222:223], v103
	s_waitcnt lgkmcnt(6)
	v_mfma_f32_16x16x32_bf16 v[98:101], v[224:227], v[60:63], v[98:101]
	s_waitcnt lgkmcnt(4)
	v_mfma_f32_16x16x32_bf16 v[196:199], v[228:231], v[60:63], v[196:199]
	s_add_i32 s1, s0, s20
	s_lshl_b32 s1, s1, 15
	s_add_i32 s0, s0, s30
	s_and_b32 s1, s1, 0x8000
	s_lshl_b32 s0, s0, 15
	s_and_b32 s0, s0, 0x8000
	s_add_i32 s1, s16, s1
	s_add_i32 s0, s31, s0
	v_add_u32_e32 v77, s1, v129
	v_add_u32_e32 v102, s0, v129
	v_add_u32_e32 v103, s1, v130
	v_add_u32_e32 v109, s0, v130
	ds_read_b64_tr_b16 v[224:225], v77
	ds_read_b64_tr_b16 v[226:227], v102
	ds_read_b64_tr_b16 v[228:229], v103
	ds_read_b64_tr_b16 v[230:231], v109
	s_waitcnt lgkmcnt(6)
	v_mfma_f32_16x16x32_bf16 v[90:93], v[90:93], v[60:63], v[94:97]
	s_waitcnt lgkmcnt(4)
	v_mfma_f32_16x16x32_bf16 v[60:63], v[220:223], v[60:63], v[64:67]
	s_nop 2
	v_add_u32_e32 v64, s1, v131
	v_add_u32_e32 v66, s0, v131
	v_add_u32_e32 v96, s0, v132
	v_add_u32_e32 v77, s1, v132
	ds_read_b64_tr_b16 v[64:65], v64
	ds_read_b64_tr_b16 v[66:67], v66
	ds_read_b64_tr_b16 v[94:95], v77
	ds_read_b64_tr_b16 v[96:97], v96
	s_waitcnt lgkmcnt(6)
	v_mfma_f32_16x16x32_bf16 v[82:85], v[224:227], v[56:59], v[82:85]
	s_waitcnt lgkmcnt(4)
	v_mfma_f32_16x16x32_bf16 v[86:89], v[228:231], v[56:59], v[86:89]
	v_add_u32_e32 v77, s1, v133
	v_add_u32_e32 v102, s0, v133
	v_add_u32_e32 v103, s1, v134
	v_add_u32_e32 v109, s0, v134
	ds_read_b64_tr_b16 v[220:221], v77
	ds_read_b64_tr_b16 v[222:223], v102
	ds_read_b64_tr_b16 v[224:225], v103
	ds_read_b64_tr_b16 v[226:227], v109
	s_waitcnt lgkmcnt(6)
	v_mfma_f32_16x16x32_bf16 v[64:67], v[64:67], v[56:59], v[68:71]
	s_waitcnt lgkmcnt(4)
	v_mfma_f32_16x16x32_bf16 v[68:71], v[94:97], v[56:59], v[78:81]
	v_add_u32_e32 v77, s1, v135
	s_nop 1
	v_add_u32_e32 v80, s0, v135
	v_add_u32_e32 v94, s1, v136
	v_add_u32_e32 v96, s0, v136
	ds_read_b64_tr_b16 v[78:79], v77
	ds_read_b64_tr_b16 v[80:81], v80
	ds_read_b64_tr_b16 v[94:95], v94
	ds_read_b64_tr_b16 v[96:97], v96
	s_waitcnt lgkmcnt(6)
	v_mfma_f32_16x16x32_bf16 v[98:101], v[220:223], v[56:59], v[98:101]
	s_waitcnt lgkmcnt(4)
	v_mfma_f32_16x16x32_bf16 v[196:199], v[224:227], v[56:59], v[196:199]
	s_waitcnt lgkmcnt(2)
	v_mfma_f32_16x16x32_bf16 v[78:81], v[78:81], v[56:59], v[90:93]
	s_waitcnt lgkmcnt(0)
	v_mfma_f32_16x16x32_bf16 v[58:61], v[94:97], v[56:59], v[60:63]
	v_add_f32_e32 v56, v75, v76
	v_div_scale_f32 v57, s[0:1], v56, v56, 1.0
	s_nop 0
	v_rcp_f32_e32 v62, v57
	v_div_scale_f32 v63, vcc, 1.0, v56, 1.0
	v_fma_f32 v75, -v57, v62, 1.0
	v_fmac_f32_e32 v62, v75, v62
	v_mul_f32_e32 v75, v63, v62
	v_fma_f32 v76, -v57, v75, v63
	v_fmac_f32_e32 v75, v76, v62
	v_fma_f32 v57, -v57, v75, v63
	v_div_fmas_f32 v57, v57, v62, v75
	v_div_fixup_f32 v57, v57, v56, 1.0
	v_lshlrev_b64 v[62:63], 12, v[72:73]
	v_mul_f32_e32 v75, v57, v82
	v_mul_f32_e32 v76, v57, v83
	v_mul_f32_e32 v77, v57, v85
	v_lshl_add_u64 v[62:63], v[126:127], 0, v[62:63]
	v_cvt_pk_bf16_f32 v76, v75, v76
	v_mul_f32_e32 v75, v57, v84
	v_cvt_pk_bf16_f32 v77, v75, v77
	global_store_dwordx2 v[62:63], v[76:77], off
	v_mul_f32_e32 v75, v57, v86
	v_mul_f32_e32 v76, v57, v87
	v_mul_f32_e32 v77, v57, v89
	v_mul_f32_e32 v64, v57, v64
	v_mul_f32_e32 v65, v57, v65
	v_cvt_pk_bf16_f32 v76, v75, v76
	v_mul_f32_e32 v75, v57, v88
	v_cvt_pk_bf16_f32 v77, v75, v77
	global_store_dwordx2 v[62:63], v[76:77], off offset:32
	v_cvt_pk_bf16_f32 v64, v64, v65
	v_mul_f32_e32 v65, v57, v66
	v_mul_f32_e32 v66, v57, v67
	v_cvt_pk_bf16_f32 v65, v65, v66
	global_store_dwordx2 v[62:63], v[64:65], off offset:64
	v_mul_f32_e32 v64, v57, v68
	v_mul_f32_e32 v65, v57, v69
	v_cvt_pk_bf16_f32 v64, v64, v65
	v_mul_f32_e32 v65, v57, v70
	v_mul_f32_e32 v66, v57, v71
	v_cvt_pk_bf16_f32 v65, v65, v66
	global_store_dwordx2 v[62:63], v[64:65], off offset:96
	v_mul_f32_e32 v64, v57, v98
	v_mul_f32_e32 v65, v57, v99
	v_cvt_pk_bf16_f32 v64, v64, v65
	v_mul_f32_e32 v65, v57, v100
	v_mul_f32_e32 v66, v57, v101
	v_cvt_pk_bf16_f32 v65, v65, v66
	global_store_dwordx2 v[62:63], v[64:65], off offset:128
	v_mul_f32_e32 v64, v57, v196
	v_mul_f32_e32 v65, v57, v197
	v_cvt_pk_bf16_f32 v64, v64, v65
	v_mul_f32_e32 v65, v57, v198
	v_mul_f32_e32 v66, v57, v199
	v_cvt_pk_bf16_f32 v65, v65, v66
	global_store_dwordx2 v[62:63], v[64:65], off offset:160
	v_mul_f32_e32 v64, v57, v78
	v_mul_f32_e32 v65, v57, v79
	v_cvt_pk_bf16_f32 v64, v64, v65
	v_mul_f32_e32 v65, v57, v80
	v_mul_f32_e32 v58, v57, v58
	v_mul_f32_e32 v59, v57, v59
	v_mul_f32_e32 v66, v57, v81
	v_cvt_pk_bf16_f32 v65, v65, v66
	global_store_dwordx2 v[62:63], v[64:65], off offset:192
	v_cvt_pk_bf16_f32 v58, v58, v59
	v_mul_f32_e32 v59, v57, v60
	v_mul_f32_e32 v57, v57, v61
	v_cvt_pk_bf16_f32 v59, v59, v57
	global_store_dwordx2 v[62:63], v[58:59], off offset:224
	s_mov_b64 s[0:1], exec
	v_readlane_b32 s10, v255, 17
	v_readlane_b32 s11, v255, 18
	s_and_b64 s[10:11], s[0:1], s[10:11]
	s_mov_b64 exec, s[10:11]
	s_cbranch_execz .LBB0_398
	v_log_f32_e32 v56, v56
	s_nop 0
	v_add_f32_e32 v58, v74, v56
	v_lshlrev_b64 v[56:57], 6, v[72:73]
	v_lshl_add_u64 v[56:57], s[12:13], 0, v[56:57]
	global_store_dword v[56:57], v58, off
